# attention epilogues (dense + memory groups): 64 two-byte O stores per wave staged through a per-wave LDS scratch and written as 8 dwordx4 row pieces
# baseline (speedup 1.0000x reference)
; __device__ __forceinline__ void finishSM(f32x16& p0, f32x16& p1, float alpha, float& l_reg, bf16x8& pa0, bf16x8& pa1, bf16x8& pa2, bf16x8& pa3) {
;   for (int r = 0; r < 16; ++r) p1[r] = __builtin_amdgcn_exp2f(p1[r]);
;   float ps = 0; for (int r = 0; r < 16; ++r) ps += p0[r]; for (int r = 0; r < 16; ++r) ps += p1[r];
;   { auto rr = __builtin_amdgcn_permlane32_swap(__float_as_uint(ps), __float_as_uint(ps), false, false);
;     ps = __uint_as_float(rr[0]) + __uint_as_float(rr[1]); }
;   l_reg = l_reg * alpha + ps;
;     ...
;   PK4(p0, 0, pa0); PK4(p0, 8, pa1); PK4(p1, 0, pa2); PK4(p1, 8, pa3);
;     ...
; }
; __device__ __forceinline__ void qkt(f32x16& p0, f32x16& p1, const bf16* Ks, const bf16x8* qr, int r32, int hi) {
;   p0 = f32x16{}; p1 = f32x16{};
;   for (int d0 = 0; d0 < 8; ++d0) { int cb = (d0 * 16 + hi * 8) * 2;
;     bf16x8 b0 = *reinterpret_cast<const bf16x8*>((const char*)Ks + KSWZ(r32, cb));
;     bf16x8 b1 = *reinterpret_cast<const bf16x8*>((const char*)Ks + KSWZ(32 + r32, cb));
;     p0 = __builtin_amdgcn_mfma_f32_32x32x16_bf16(b0, qr[d0], p0, 0, 0, 0);
;     p1 = __builtin_amdgcn_mfma_f32_32x32x16_bf16(b1, qr[d0], p1, 0, 0, 0); }
; }
; __device__ __forceinline__ int v_st(int k, int c) { const int kk = (k & ~0xC) | ((k & 4) << 1) | ((k & 8) >> 1); return ((kk >> 3) * 4 + (c >> 5)) * 512 + ((kk & 7) * 32 + (c & 31)) * 2; }
; __device__ __forceinline__ int v_rd_base(int lane) { return ((lane & 3) << 3) | (((lane >> 2) & 3) << 6) | (((lane >> 4) & 1) << 5) | (((lane >> 5) & 1) << 8); }
; template <int OFF> __device__ __forceinline__ s16x4 tr_read(int vb) {
;   s16x4 r; asm volatile("ds_read_b64_tr_b16 %0, %1 offset:%2" : "=&v"(r) : "v"(vb), "i"(OFF) : "memory"); return r;
; }
; template <int D0> __device__ __forceinline__ void pv_one(f32x16& od, int vb, bf16x8 pa0, bf16x8 pa1, bf16x8 pa2, bf16x8 pa3) {
;   const s16x4 l0 = tr_read<v_rd_off(D0, 0, 0)>(vb), h0 = tr_read<v_rd_off(D0, 0, 1)>(vb), l1 = tr_read<v_rd_off(D0, 1, 0)>(vb), h1 = tr_read<v_rd_off(D0, 1, 1)>(vb);
;   const s16x4 l2 = tr_read<v_rd_off(D0, 2, 0)>(vb), h2 = tr_read<v_rd_off(D0, 2, 1)>(vb), l3 = tr_read<v_rd_off(D0, 3, 0)>(vb), h3 = tr_read<v_rd_off(D0, 3, 1)>(vb);
;   asm volatile("s_waitcnt lgkmcnt(0)" ::: "memory"); SBAR();
;     ...
;   od = __builtin_amdgcn_mfma_f32_32x32x16_bf16(pa0, PK(l0, h0), od, 0, 0, 0);
;   od = __builtin_amdgcn_mfma_f32_32x32x16_bf16(pa1, PK(l1, h1), od, 0, 0, 0);
.LBB0_187:
	v_exp_f32_e32 v98, v66
	v_add_f32_e32 v66, 0, v82
	v_add_f32_e32 v66, v83, v66
	v_add_f32_e32 v66, v84, v66
	v_add_f32_e32 v66, v85, v66
	v_add_f32_e32 v66, v86, v66
	v_add_f32_e32 v66, v87, v66
	v_add_f32_e32 v66, v88, v66
	v_add_f32_e32 v66, v89, v66
	v_add_f32_e32 v66, v90, v66
	v_add_f32_e32 v66, v91, v66
	v_add_f32_e32 v66, v92, v66
	v_add_f32_e32 v66, v93, v66
	v_add_f32_e32 v66, v94, v66
	v_exp_f32_e32 v99, v67
	v_add_f32_e32 v66, v95, v66
	v_exp_f32_e32 v100, v68
	v_add_f32_e32 v66, v96, v66
	v_exp_f32_e32 v101, v69
	v_add_f32_e32 v66, v97, v66
	v_exp_f32_e32 v102, v70
	v_add_f32_e32 v66, v98, v66
	v_exp_f32_e32 v103, v71
	v_add_f32_e32 v66, v99, v66
	v_exp_f32_e32 v104, v72
	v_add_f32_e32 v66, v100, v66
	v_exp_f32_e32 v105, v73
	v_add_f32_e32 v66, v101, v66
	v_exp_f32_e32 v106, v74
	v_add_f32_e32 v66, v102, v66
	v_exp_f32_e32 v107, v75
	v_add_f32_e32 v66, v103, v66
	v_exp_f32_e32 v108, v76
	v_add_f32_e32 v66, v104, v66
	v_exp_f32_e32 v109, v77
	v_add_f32_e32 v66, v105, v66
	v_exp_f32_e32 v110, v78
	v_add_f32_e32 v66, v106, v66
	v_exp_f32_e32 v111, v79
	v_add_f32_e32 v66, v107, v66
	v_exp_f32_e32 v112, v80
	v_add_f32_e32 v66, v108, v66
	v_exp_f32_e32 v113, v81
	v_add_f32_e32 v66, v109, v66
	v_add_f32_e32 v66, v110, v66
	v_add_f32_e32 v66, v111, v66
	v_add_f32_e32 v66, v112, v66
	v_add_f32_e32 v66, v113, v66
	v_mov_b32_e32 v67, v66
	s_nop 1
	v_permlane32_swap_b32_e32 v66, v67
	v_cvt_pk_bf16_f32 v68, v82, v83
	v_cvt_pk_bf16_f32 v69, v84, v85
	v_cvt_pk_bf16_f32 v70, v86, v87
	v_cvt_pk_bf16_f32 v71, v88, v89
	v_cvt_pk_bf16_f32 v72, v90, v91
	v_cvt_pk_bf16_f32 v73, v92, v93
	v_cvt_pk_bf16_f32 v74, v94, v95
	v_cvt_pk_bf16_f32 v75, v96, v97
	v_cvt_pk_bf16_f32 v76, v98, v99
	v_cvt_pk_bf16_f32 v77, v100, v101
	v_cvt_pk_bf16_f32 v78, v102, v103
	v_cvt_pk_bf16_f32 v79, v104, v105
	v_cvt_pk_bf16_f32 v80, v106, v107
	v_cvt_pk_bf16_f32 v81, v108, v109
	v_cvt_pk_bf16_f32 v82, v110, v111
	v_cvt_pk_bf16_f32 v83, v112, v113
	s_nop 0
	v_permlane32_swap_b32_e32 v68, v70
	v_permlane32_swap_b32_e32 v69, v71
	v_permlane32_swap_b32_e32 v72, v74
	v_permlane32_swap_b32_e32 v73, v75
	v_permlane32_swap_b32_e32 v76, v78
	v_permlane32_swap_b32_e32 v77, v79
	v_permlane32_swap_b32_e32 v80, v82
	v_permlane32_swap_b32_e32 v81, v83
	ds_read_b64_tr_b16 v[84:85], v216 offset:0
	ds_read_b64_tr_b16 v[86:87], v216 offset:0x800
	ds_read_b64_tr_b16 v[88:89], v216 offset:0x1000
	ds_read_b64_tr_b16 v[90:91], v216 offset:0x1800
	ds_read_b64_tr_b16 v[92:93], v216 offset:0x2000
	ds_read_b64_tr_b16 v[94:95], v216 offset:0x2800
	ds_read_b64_tr_b16 v[96:97], v216 offset:0x3000
	ds_read_b64_tr_b16 v[98:99], v216 offset:0x3800
	s_waitcnt lgkmcnt(0)
	s_nop 0
	v_mfma_f32_32x32x16_bf16 v[50:65], v[68:71], v[84:87], v[50:65]
	ds_read_b64_tr_b16 v[84:85], v216 offset:0x200
	ds_read_b64_tr_b16 v[86:87], v216 offset:0xa00
	v_mfma_f32_32x32x16_bf16 v[50:65], v[72:75], v[88:91], v[50:65]
	ds_read_b64_tr_b16 v[88:89], v216 offset:0x1200
	ds_read_b64_tr_b16 v[90:91], v216 offset:0x1a00
	v_mfma_f32_32x32x16_bf16 v[50:65], v[76:79], v[92:95], v[50:65]
	ds_read_b64_tr_b16 v[92:93], v216 offset:0x2200
	ds_read_b64_tr_b16 v[94:95], v216 offset:0x2a00
	ds_read_b64_tr_b16 v[100:101], v216 offset:0x3200
	ds_read_b64_tr_b16 v[102:103], v216 offset:0x3a00
	s_waitcnt lgkmcnt(0)
	v_mfma_f32_32x32x16_bf16 v[50:65], v[80:83], v[96:99], v[50:65]
	v_mfma_f32_32x32x16_bf16 v[34:49], v[68:71], v[84:87], v[34:49]
	ds_read_b64_tr_b16 v[84:85], v216 offset:0x400
	ds_read_b64_tr_b16 v[86:87], v216 offset:0xc00
	v_mfma_f32_32x32x16_bf16 v[34:49], v[72:75], v[88:91], v[34:49]
	ds_read_b64_tr_b16 v[88:89], v216 offset:0x1400
	ds_read_b64_tr_b16 v[90:91], v216 offset:0x1c00
	v_mfma_f32_32x32x16_bf16 v[34:49], v[76:79], v[92:95], v[34:49]
	ds_read_b64_tr_b16 v[92:93], v216 offset:0x2400
	ds_read_b64_tr_b16 v[94:95], v216 offset:0x2c00
	ds_read_b64_tr_b16 v[96:97], v216 offset:0x3400
	ds_read_b64_tr_b16 v[98:99], v216 offset:0x3c00
	s_waitcnt lgkmcnt(0)
	v_mfma_f32_32x32x16_bf16 v[34:49], v[80:83], v[100:103], v[34:49]
	v_mfma_f32_32x32x16_bf16 v[18:33], v[68:71], v[84:87], v[18:33]
	ds_read_b64_tr_b16 v[84:85], v216 offset:0x600
	ds_read_b64_tr_b16 v[86:87], v216 offset:0xe00
	v_mfma_f32_32x32x16_bf16 v[18:33], v[72:75], v[88:91], v[18:33]
	ds_read_b64_tr_b16 v[88:89], v216 offset:0x1600
	ds_read_b64_tr_b16 v[90:91], v216 offset:0x1e00
	v_mfma_f32_32x32x16_bf16 v[18:33], v[76:79], v[92:95], v[18:33]
	ds_read_b64_tr_b16 v[92:93], v216 offset:0x2600
	ds_read_b64_tr_b16 v[94:95], v216 offset:0x2e00
	ds_read_b64_tr_b16 v[100:101], v216 offset:0x3600
	ds_read_b64_tr_b16 v[102:103], v216 offset:0x3e00
	s_waitcnt lgkmcnt(0)
	v_mfma_f32_32x32x16_bf16 v[18:33], v[80:83], v[96:99], v[18:33]
	v_mfma_f32_32x32x16_bf16 v[2:17], v[68:71], v[84:87], v[2:17]
	v_mfma_f32_32x32x16_bf16 v[2:17], v[72:75], v[88:91], v[2:17]
	v_mfma_f32_32x32x16_bf16 v[2:17], v[76:79], v[92:95], v[2:17]
	v_mfma_f32_32x32x16_bf16 v[2:17], v[80:83], v[100:103], v[2:17]
	s_setprio 0
	s_and_saveexec_b64 s[16:17], s[2:3]
	v_add_f32_e32 v68, v150, v151
	v_fmac_f32_e32 v68, v215, v236
	v_add_f32_e32 v66, v66, v67
	v_fmac_f32_e32 v66, v68, v146
	ds_write_b32 v214, v66
	s_or_b64 exec, exec, s[16:17]
	s_waitcnt lgkmcnt(0)
	v_add_u32_e32 v74, s95, v210
	ds_read_b128 v[66:69], v74
	ds_read_b128 v[70:73], v74 offset:32
	s_lshl_b64 s[2:3], s[8:9], 12
	s_add_u32 s2, s74, s2
	s_addc_u32 s3, s75, s3
	s_waitcnt lgkmcnt(1)
	v_rcp_f32_e32 v75, v66
	v_rcp_f32_e32 v76, v67
	v_rcp_f32_e32 v78, v68
	v_rcp_f32_e32 v80, v69
	ds_read_b128 v[66:69], v74 offset:64
	s_lshl_b32 s4, s47, 1
	s_add_u32 s4, s2, s4
	s_addc_u32 s5, s3, 0
	s_lshl_b64 s[2:3], s[8:9], 6
	s_add_u32 s8, s10, s2
	s_addc_u32 s16, s11, s3
	s_lshl_b64 s[2:3], s[48:49], 2
	s_waitcnt lgkmcnt(1)
; __device__ __forceinline__ int crow(int r, int hi) { return (r & 3) + 8 * (r >> 2) + 4 * hi; }
; template <int MODE, int QMODE> ...
;     ...
;   if (hi == 0) li_l[r32] = l_reg; asm volatile("s_waitcnt lgkmcnt(0)" ::: "memory");
;   float rli[16];
; #pragma unroll
;   for (int r = 0; r < 16; ++r) rli[r] = __builtin_amdgcn_rcpf(li_l[crow(r, hi)]);
;   unsigned zz_ = 0u; asm volatile("" : "+v"(zz_)); const int r32e = (int)__builtin_amdgcn_mbcnt_hi(~0u, __builtin_amdgcn_mbcnt_lo(~0u, zz_)) & 31;
;   unsigned short* Ow = Ob + (long)wrow * LDO + wcol + r32e;
; #pragma unroll
;   for (int r = 0; r < 16; ++r) { int orow = crow(r, hi);
; #pragma unroll
;     for (int d0 = 0; d0 < 4; ++d0) { const float v = o[d0][r] * rli[r]; Ow[(long)orow * LDO + d0 * 32] = (unsigned short)(cvtpk(v, v) & 0xffffu); o[d0][r] = v * v; } }
	v_rcp_f32_e32 v89, v70
	v_rcp_f32_e32 v90, v71
	v_rcp_f32_e32 v91, v72
	v_rcp_f32_e32 v92, v73
	ds_read_b128 v[70:73], v74 offset:96
	s_waitcnt lgkmcnt(1)
	v_rcp_f32_e32 v93, v66
	v_mov_b32_e32 v66, v211
	s_add_u32 s2, s8, s2
	s_addc_u32 s3, s16, s3
	v_mbcnt_lo_u32_b32 v66, -1, v66
	s_ashr_i32 s47, s46, 31
	v_mbcnt_hi_u32_b32 v66, -1, v66
	s_lshl_b64 s[16:17], s[46:47], 12
	v_rcp_f32_e32 v95, v68
	v_and_b32_e32 v68, 31, v66
	s_add_u32 s16, s4, s16
	s_addc_u32 s17, s5, s17
	v_lshlrev_b32_e32 v210, 1, v68
	v_rcp_f32_e32 v94, v67
	v_lshl_add_u64 v[66:67], s[16:17], 0, v[210:211]
	v_lshlrev_b32_e32 v210, 14, v226
	v_lshl_add_u64 v[66:67], v[66:67], 0, v[210:211]
	v_mul_f32_e32 v101, v50, v75
	v_cvt_pk_bf16_f32 v50, v101, v101
	v_readfirstlane_b32 s98, v66
	v_readfirstlane_b32 s99, v67
	v_readfirstlane_b32 s100, v0
	v_mbcnt_lo_u32_b32 v209, -1, 0
	v_mbcnt_hi_u32_b32 v209, -1, v209
	s_lshr_b32 s100, s100, 6
	s_lshl_b32 s100, s100, 13
	s_add_i32 s100, s100, 0x10800
	v_lshrrev_b32_e32 v206, 5, v209
	v_and_b32_e32 v207, 31, v209
	v_lshlrev_b32_e32 v206, 10, v206
	v_lshl_add_u32 v206, v207, 1, v206
	v_add_u32_e32 v206, s100, v206
	ds_write_b16 v206, v50 offset:0
	v_mul_f32_e32 v34, v34, v75
	v_cvt_pk_bf16_f32 v50, v34, v34
	ds_write_b16 v206, v50 offset:64
	v_mul_f32_e32 v103, v18, v75
	v_cvt_pk_bf16_f32 v18, v103, v103
	v_mul_f32_e32 v2, v2, v75
	v_add_co_u32_e32 v50, vcc, s60, v66
	ds_write_b16 v206, v18 offset:128
	v_cvt_pk_bf16_f32 v18, v2, v2
	ds_write_b16 v206, v18 offset:192
	v_mul_f32_e32 v104, v2, v2
	v_mul_f32_e32 v81, v51, v76
	v_cvt_pk_bf16_f32 v2, v81, v81
	v_addc_co_u32_e32 v51, vcc, 0, v67, vcc
	ds_write_b16 v206, v2 offset:256
	v_mul_f32_e32 v86, v35, v76
	v_cvt_pk_bf16_f32 v2, v86, v86
	ds_write_b16 v206, v2 offset:320
	v_mul_f32_e32 v85, v19, v76
	v_cvt_pk_bf16_f32 v2, v85, v85
	ds_write_b16 v206, v2 offset:384
	v_mul_f32_e32 v88, v3, v76
	v_cvt_pk_bf16_f32 v2, v88, v88
	ds_write_b16 v206, v2 offset:448
	v_add_co_u32_e32 v2, vcc, s51, v66
	v_mul_f32_e32 v77, v52, v78
	v_cvt_pk_bf16_f32 v18, v77, v77
	s_nop 0
	v_addc_co_u32_e32 v3, vcc, 0, v67, vcc
	ds_write_b16 v206, v18 offset:512
	v_mul_f32_e32 v83, v36, v78
	v_cvt_pk_bf16_f32 v18, v83, v83
	ds_write_b16 v206, v18 offset:576
	v_mul_f32_e32 v82, v20, v78
	v_cvt_pk_bf16_f32 v18, v82, v82
	ds_write_b16 v206, v18 offset:640
	v_mul_f32_e32 v87, v4, v78
	v_cvt_pk_bf16_f32 v4, v87, v87
	ds_write_b16 v206, v4 offset:704
	v_add_co_u32_e32 v2, vcc, s81, v66
	s_waitcnt lgkmcnt(0)
	v_rcp_f32_e32 v100, v73
	v_mul_f32_e32 v73, v53, v80
	v_cvt_pk_bf16_f32 v4, v73, v73
	v_addc_co_u32_e32 v3, vcc, 0, v67, vcc
	ds_write_b16 v206, v4 offset:768
	v_mul_f32_e32 v79, v37, v80
	v_cvt_pk_bf16_f32 v4, v79, v79
	ds_write_b16 v206, v4 offset:832
	v_mul_f32_e32 v78, v21, v80
	v_cvt_pk_bf16_f32 v4, v78, v78
	ds_write_b16 v206, v4 offset:896
	v_mul_f32_e32 v84, v5, v80
	v_cvt_pk_bf16_f32 v4, v84, v84
	ds_write_b16 v206, v4 offset:960
	v_add_co_u32_e32 v2, vcc, s82, v66
	v_rcp_f32_e32 v96, v69
	v_mul_f32_e32 v69, v54, v89
	v_cvt_pk_bf16_f32 v4, v69, v69
	v_addc_co_u32_e32 v3, vcc, 0, v67, vcc
	ds_write_b16 v206, v4 offset:2048
	v_mul_f32_e32 v75, v38, v89
	v_cvt_pk_bf16_f32 v4, v75, v75
	ds_write_b16 v206, v4 offset:2112
	v_mul_f32_e32 v74, v22, v89
	v_cvt_pk_bf16_f32 v4, v74, v74
	ds_write_b16 v206, v4 offset:2176
	v_mul_f32_e32 v80, v6, v89
	v_cvt_pk_bf16_f32 v4, v80, v80
	ds_write_b16 v206, v4 offset:2240
	v_add_co_u32_e32 v2, vcc, s83, v66
	v_mul_f32_e32 v53, v55, v90
	v_cvt_pk_bf16_f32 v4, v53, v53
	s_nop 0
	v_addc_co_u32_e32 v3, vcc, 0, v67, vcc
	v_rcp_f32_e32 v98, v71
	ds_write_b16 v206, v4 offset:2304
	v_mul_f32_e32 v71, v39, v90
	v_cvt_pk_bf16_f32 v4, v71, v71
	v_rcp_f32_e32 v97, v70
	ds_write_b16 v206, v4 offset:2368
	v_mul_f32_e32 v70, v23, v90
	v_cvt_pk_bf16_f32 v4, v70, v70
	ds_write_b16 v206, v4 offset:2432
	v_mul_f32_e32 v76, v7, v90
	v_cvt_pk_bf16_f32 v4, v76, v76
	ds_write_b16 v206, v4 offset:2496
	v_add_co_u32_e32 v2, vcc, s84, v66
	v_mul_f32_e32 v50, v56, v91
	v_cvt_pk_bf16_f32 v4, v50, v50
	s_nop 0
	v_addc_co_u32_e32 v3, vcc, 0, v67, vcc
	ds_write_b16 v206, v4 offset:2560
	v_mul_f32_e32 v55, v40, v91
	v_cvt_pk_bf16_f32 v4, v55, v55
	ds_write_b16 v206, v4 offset:2624
	v_mul_f32_e32 v54, v24, v91
	v_cvt_pk_bf16_f32 v4, v54, v54
	v_rcp_f32_e32 v99, v72
	ds_write_b16 v206, v4 offset:2688
	v_mul_f32_e32 v72, v8, v91
	v_cvt_pk_bf16_f32 v4, v72, v72
	ds_write_b16 v206, v4 offset:2752
	v_add_co_u32_e32 v2, vcc, s85, v66
	v_mul_f32_e32 v38, v57, v92
	v_cvt_pk_bf16_f32 v4, v38, v38
	s_nop 0
	v_addc_co_u32_e32 v3, vcc, 0, v67, vcc
	ds_write_b16 v206, v4 offset:2816
	v_mul_f32_e32 v52, v41, v92
	v_cvt_pk_bf16_f32 v4, v52, v52
	ds_write_b16 v206, v4 offset:2880
	v_mul_f32_e32 v51, v25, v92
	v_cvt_pk_bf16_f32 v4, v51, v51
	ds_write_b16 v206, v4 offset:2944
	v_mul_f32_e32 v56, v9, v92
	v_cvt_pk_bf16_f32 v4, v56, v56
	ds_write_b16 v206, v4 offset:3008
	v_add_co_u32_e32 v2, vcc, s58, v66
	v_mul_f32_e32 v102, v34, v34
	v_mul_f32_e32 v34, v58, v93
	v_cvt_pk_bf16_f32 v4, v34, v34
	v_addc_co_u32_e32 v3, vcc, 0, v67, vcc
	ds_write_b16 v206, v4 offset:4096
	v_mul_f32_e32 v40, v42, v93
	v_cvt_pk_bf16_f32 v4, v40, v40
	ds_write_b16 v206, v4 offset:4160
	v_mul_f32_e32 v39, v26, v93
	v_cvt_pk_bf16_f32 v4, v39, v39
	ds_write_b16 v206, v4 offset:4224
	v_mul_f32_e32 v42, v10, v93
	v_cvt_pk_bf16_f32 v4, v42, v42
	ds_write_b16 v206, v4 offset:4288
	v_add_co_u32_e32 v2, vcc, s86, v66
	v_mul_f32_e32 v25, v59, v94
; __device__ __forceinline__ int crow(int r, int hi) { return (r & 3) + 8 * (r >> 2) + 4 * hi; }
; template <int MODE, int QMODE> ...
;     ...
;   for (int r = 0; r < 16; ++r) { int orow = crow(r, hi);
; #pragma unroll
;     for (int d0 = 0; d0 < 4; ++d0) { const float v = o[d0][r] * rli[r]; Ow[(long)orow * LDO + d0 * 32] = (unsigned short)(cvtpk(v, v) & 0xffffu); o[d0][r] = v * v; } }
;   { float* hw = hsp + (long)wrow * 16 + (MODE ? (wid >> 2) : 0);
; #pragma unroll
;     for (int r = 0; r < 16; ++r) { float q = (o[0][r] + o[1][r]) + (o[2][r] + o[3][r]);
;       q += __builtin_bit_cast(float, __builtin_amdgcn_update_dpp(0, __builtin_bit_cast(int, q), 0xB1, 0xF, 0xF, true));
;       q += __builtin_bit_cast(float, __builtin_amdgcn_update_dpp(0, __builtin_bit_cast(int, q), 0x4E, 0xF, 0xF, true));
;       q += __builtin_bit_cast(float, __builtin_amdgcn_update_dpp(0, __builtin_bit_cast(int, q), 0x141, 0xF, 0xF, true));
;       q += __builtin_bit_cast(float, __builtin_amdgcn_update_dpp(0, __builtin_bit_cast(int, q), 0x140, 0xF, 0xF, true));
;       { float q2 = q; asm volatile("" : "+v"(q2)); auto rr = __builtin_amdgcn_permlane16_swap(__float_as_uint(q), __float_as_uint(q2), false, false); const unsigned a_ = rr[0], b_ = rr[1]; q = __uint_as_float(a_) + __uint_as_float(b_); }
;       if (r32e == r) hw[(long)crow(r, hi) * 16] = q; } }
	v_cvt_pk_bf16_f32 v4, v25, v25
	s_nop 0
	v_addc_co_u32_e32 v3, vcc, 0, v67, vcc
	ds_write_b16 v206, v4 offset:4352
	v_mul_f32_e32 v36, v43, v94
	v_cvt_pk_bf16_f32 v4, v36, v36
	ds_write_b16 v206, v4 offset:4416
	v_mul_f32_e32 v35, v27, v94
	v_cvt_pk_bf16_f32 v4, v35, v35
	ds_write_b16 v206, v4 offset:4480
	v_mul_f32_e32 v41, v11, v94
	v_cvt_pk_bf16_f32 v4, v41, v41
	ds_write_b16 v206, v4 offset:4544
	v_add_co_u32_e32 v2, vcc, s87, v66
	v_mul_f32_e32 v21, v60, v95
	v_cvt_pk_bf16_f32 v4, v21, v21
	s_nop 0
	v_addc_co_u32_e32 v3, vcc, 0, v67, vcc
	ds_write_b16 v206, v4 offset:4608
	v_mul_f32_e32 v27, v44, v95
	v_cvt_pk_bf16_f32 v4, v27, v27
	ds_write_b16 v206, v4 offset:4672
	v_mul_f32_e32 v26, v28, v95
	v_cvt_pk_bf16_f32 v4, v26, v26
	ds_write_b16 v206, v4 offset:4736
	v_mul_f32_e32 v37, v12, v95
	v_cvt_pk_bf16_f32 v4, v37, v37
	ds_write_b16 v206, v4 offset:4800
	v_add_co_u32_e32 v2, vcc, s88, v66
	v_mul_f32_e32 v18, v61, v96
	v_cvt_pk_bf16_f32 v4, v18, v18
	s_nop 0
	v_addc_co_u32_e32 v3, vcc, 0, v67, vcc
	ds_write_b16 v206, v4 offset:4864
	v_mul_f32_e32 v23, v45, v96
	v_cvt_pk_bf16_f32 v4, v23, v23
	ds_write_b16 v206, v4 offset:4928
	v_mul_f32_e32 v22, v29, v96
	v_cvt_pk_bf16_f32 v4, v22, v22
	ds_write_b16 v206, v4 offset:4992
	v_mul_f32_e32 v28, v13, v96
	v_cvt_pk_bf16_f32 v4, v28, v28
	ds_write_b16 v206, v4 offset:5056
	v_add_co_u32_e32 v2, vcc, s89, v66
	v_mul_f32_e32 v11, v62, v97
	v_cvt_pk_bf16_f32 v4, v11, v11
	s_nop 0
	v_addc_co_u32_e32 v3, vcc, 0, v67, vcc
	ds_write_b16 v206, v4 offset:6144
	v_mul_f32_e32 v20, v46, v97
	v_cvt_pk_bf16_f32 v4, v20, v20
	ds_write_b16 v206, v4 offset:6208
	v_mul_f32_e32 v19, v30, v97
	v_cvt_pk_bf16_f32 v4, v19, v19
	ds_write_b16 v206, v4 offset:6272
	v_mul_f32_e32 v24, v14, v97
	v_cvt_pk_bf16_f32 v4, v24, v24
	ds_write_b16 v206, v4 offset:6336
	v_add_co_u32_e32 v2, vcc, s90, v66
	v_mul_f32_e32 v7, v63, v98
	v_cvt_pk_bf16_f32 v4, v7, v7
	s_nop 0
	v_addc_co_u32_e32 v3, vcc, 0, v67, vcc
	ds_write_b16 v206, v4 offset:6400
	v_mul_f32_e32 v13, v47, v98
	v_cvt_pk_bf16_f32 v4, v13, v13
	ds_write_b16 v206, v4 offset:6464
	v_mul_f32_e32 v12, v31, v98
	v_cvt_pk_bf16_f32 v4, v12, v12
	ds_write_b16 v206, v4 offset:6528
	v_mul_f32_e32 v15, v15, v98
	v_cvt_pk_bf16_f32 v4, v15, v15
	ds_write_b16 v206, v4 offset:6592
	v_add_co_u32_e32 v2, vcc, s91, v66
	v_fmac_f32_e32 v102, v101, v101
	v_fmac_f32_e32 v104, v103, v103
	v_mul_f32_e32 v4, v64, v99
	v_cvt_pk_bf16_f32 v5, v4, v4
	v_addc_co_u32_e32 v3, vcc, 0, v67, vcc
	v_mul_f32_e32 v14, v16, v99
	v_add_f32_e32 v16, v102, v104
	ds_write_b16 v206, v5 offset:6656
	v_mul_f32_e32 v9, v48, v99
	v_cvt_pk_bf16_f32 v5, v9, v9
	v_add_f32_dpp v16, v16, v16 quad_perm:[1,0,3,2] row_mask:0xf bank_mask:0xf bound_ctrl:1
	ds_write_b16 v206, v5 offset:6720
	v_mul_f32_e32 v8, v32, v99
	v_cvt_pk_bf16_f32 v5, v8, v8
	v_add_co_u32_e32 v30, vcc, s92, v66
	v_add_f32_dpp v16, v16, v16 quad_perm:[2,3,0,1] row_mask:0xf bank_mask:0xf bound_ctrl:1
	ds_write_b16 v206, v5 offset:6784
	v_cvt_pk_bf16_f32 v5, v14, v14
	ds_write_b16 v206, v5 offset:6848
	v_mul_f32_e32 v2, v65, v100
	v_cvt_pk_bf16_f32 v3, v2, v2
	v_addc_co_u32_e32 v31, vcc, 0, v67, vcc
	v_add_f32_dpp v16, v16, v16 row_half_mirror row_mask:0xf bank_mask:0xf bound_ctrl:1
	ds_write_b16 v206, v3 offset:6912
	v_mul_f32_e32 v6, v49, v100
	v_cvt_pk_bf16_f32 v3, v6, v6
	v_add_f32_dpp v16, v16, v16 row_mirror row_mask:0xf bank_mask:0xf bound_ctrl:1
	ds_write_b16 v206, v3 offset:6976
	v_mul_f32_e32 v5, v33, v100
	v_cvt_pk_bf16_f32 v3, v5, v5
	v_mul_f32_e32 v10, v17, v100
	s_lshl_b64 s[16:17], s[46:47], 6
	v_mov_b32_e32 v17, v16
	ds_write_b16 v206, v3 offset:7040
	v_cvt_pk_bf16_f32 v3, v10, v10
	ds_write_b16 v206, v3 offset:7104
	v_lshl_add_u32 v207, v209, 4, s100
	v_lshrrev_b32_e32 v208, 4, v209
	v_and_b32_e32 v209, 15, v209
	v_lshlrev_b32_e32 v208, 12, v208
	v_lshl_add_u32 v208, v209, 4, v208
	s_waitcnt lgkmcnt(0)
	ds_read_b128 v[174:177], v207 offset:0
	ds_read_b128 v[178:181], v207 offset:1024
	ds_read_b128 v[182:185], v207 offset:2048
	ds_read_b128 v[186:189], v207 offset:3072
	ds_read_b128 v[190:193], v207 offset:4096
	ds_read_b128 v[194:197], v207 offset:5120
	ds_read_b128 v[198:201], v207 offset:6144
	ds_read_b128 v[202:205], v207 offset:7168
	s_waitcnt lgkmcnt(7)
	global_store_dwordx4 v208, v[174:177], s[98:99] offset:2048
	v_add_u32_e32 v208, 0x4000, v208
	s_waitcnt lgkmcnt(6)
	global_store_dwordx4 v208, v[178:181], s[98:99] offset:2048
	v_add_u32_e32 v208, 0x4000, v208
	s_waitcnt lgkmcnt(5)
	global_store_dwordx4 v208, v[182:185], s[98:99] offset:2048
	v_add_u32_e32 v208, 0x4000, v208
	s_waitcnt lgkmcnt(4)
	global_store_dwordx4 v208, v[186:189], s[98:99] offset:2048
	v_add_u32_e32 v208, 0x4000, v208
	s_waitcnt lgkmcnt(3)
	global_store_dwordx4 v208, v[190:193], s[98:99] offset:2048
	v_add_u32_e32 v208, 0x4000, v208
	s_waitcnt lgkmcnt(2)
	global_store_dwordx4 v208, v[194:197], s[98:99] offset:2048
	v_add_u32_e32 v208, 0x4000, v208
	s_waitcnt lgkmcnt(1)
	global_store_dwordx4 v208, v[198:201], s[98:99] offset:2048
	v_add_u32_e32 v208, 0x4000, v208
	s_waitcnt lgkmcnt(0)
	global_store_dwordx4 v208, v[202:205], s[98:99] offset:2048
	s_nop 1
	s_add_u32 s2, s2, s16
	s_addc_u32 s3, s3, s17
	v_lshlrev_b32_e32 v3, 8, v226
	v_permlane16_swap_b32_e32 v16, v17
	v_cmp_eq_u32_e32 vcc, 0, v68
	s_and_saveexec_b64 s[16:17], vcc
	s_cbranch_execz .LBB0_191
	v_add_f32_e32 v16, v16, v17
	global_store_dword v3, v16, s[2:3] offset:32

; __device__ __forceinline__ int crow(int r, int hi) { return (r & 3) + 8 * (r >> 2) + 4 * hi; }
; template <int MODE, int QMODE> ...
;     ...
;   if (hi == 0) li_l[r32] = l_reg; asm volatile("s_waitcnt lgkmcnt(0)" ::: "memory");
;   float rli[16];
; #pragma unroll
;   for (int r = 0; r < 16; ++r) rli[r] = __builtin_amdgcn_rcpf(li_l[crow(r, hi)]);
;   unsigned zz_ = 0u; asm volatile("" : "+v"(zz_)); const int r32e = (int)__builtin_amdgcn_mbcnt_hi(~0u, __builtin_amdgcn_mbcnt_lo(~0u, zz_)) & 31;
;   unsigned short* Ow = Ob + (long)wrow * LDO + wcol + r32e;
; #pragma unroll
;   for (int r = 0; r < 16; ++r) { int orow = crow(r, hi);
; #pragma unroll
;     for (int d0 = 0; d0 < 4; ++d0) { const float v = o[d0][r] * rli[r]; Ow[(long)orow * LDO + d0 * 32] = (unsigned short)(cvtpk(v, v) & 0xffffu); o[d0][r] = v * v; } }
.LBB0_306:
	s_or_b64 exec, exec, s[20:21]
	s_waitcnt lgkmcnt(0)
	v_add_u32_e32 v74, s59, v194
	ds_read_b128 v[66:69], v74
	ds_read_b128 v[70:73], v74 offset:32
	s_lshl_b64 s[2:3], s[18:19], 12
	s_add_u32 s2, s74, s2
	s_addc_u32 s3, s75, s3
	s_waitcnt lgkmcnt(1)
	v_rcp_f32_e32 v75, v66
	v_rcp_f32_e32 v76, v67
	v_rcp_f32_e32 v78, v68
	v_rcp_f32_e32 v80, v69
	ds_read_b128 v[66:69], v74 offset:64
	s_add_u32 s8, s2, s8
	s_addc_u32 s20, s3, 0
	s_lshl_b64 s[2:3], s[18:19], 6
	s_add_u32 s2, s10, s2
	s_addc_u32 s3, s11, s3
	s_lshl_b32 s4, s17, 2
	s_waitcnt lgkmcnt(1)
	v_rcp_f32_e32 v89, v70
	v_rcp_f32_e32 v90, v71
	v_rcp_f32_e32 v91, v72
	v_rcp_f32_e32 v92, v73
	ds_read_b128 v[70:73], v74 offset:96
	s_waitcnt lgkmcnt(1)
	v_rcp_f32_e32 v93, v66
	v_mov_b32_e32 v66, v195
	s_add_u32 s2, s2, s4
	s_addc_u32 s3, s3, 0
	v_mbcnt_lo_u32_b32 v66, -1, v66
	s_ashr_i32 s17, s16, 31
	v_mbcnt_hi_u32_b32 v66, -1, v66
	s_lshl_b64 s[4:5], s[16:17], 12
	v_rcp_f32_e32 v95, v68
	v_and_b32_e32 v68, 31, v66
	s_add_u32 s4, s8, s4
	s_addc_u32 s5, s20, s5
	v_lshlrev_b32_e32 v194, 1, v68
	v_rcp_f32_e32 v94, v67
	v_lshl_add_u64 v[66:67], s[4:5], 0, v[194:195]
	v_lshlrev_b32_e32 v194, 14, v196
	v_lshl_add_u64 v[66:67], v[66:67], 0, v[194:195]
	v_mul_f32_e32 v101, v2, v75
	v_cvt_pk_bf16_f32 v2, v101, v101
	v_readfirstlane_b32 s98, v66
	v_readfirstlane_b32 s99, v67
	v_readfirstlane_b32 s100, v0
	v_mbcnt_lo_u32_b32 v249, -1, 0
	v_mbcnt_hi_u32_b32 v249, -1, v249
	s_lshr_b32 s100, s100, 6
	s_lshl_b32 s100, s100, 13
	s_add_i32 s100, s100, 0x10800
	v_lshrrev_b32_e32 v246, 5, v249
	v_and_b32_e32 v247, 31, v249
	v_lshlrev_b32_e32 v246, 10, v246
	v_lshl_add_u32 v246, v247, 1, v246
	v_add_u32_e32 v246, s100, v246
	ds_write_b16 v246, v2 offset:0
	v_mul_f32_e32 v2, v18, v75
	v_cvt_pk_bf16_f32 v18, v2, v2
	ds_write_b16 v246, v18 offset:64
	v_mul_f32_e32 v102, v2, v2
	v_mul_f32_e32 v103, v34, v75
	v_cvt_pk_bf16_f32 v2, v103, v103
	ds_write_b16 v246, v2 offset:128
	v_mul_f32_e32 v2, v50, v75
	v_cvt_pk_bf16_f32 v18, v2, v2
	v_mul_f32_e32 v104, v2, v2
	v_add_co_u32_e32 v2, vcc, s44, v66
	ds_write_b16 v246, v18 offset:192
	v_mul_f32_e32 v81, v3, v76
	v_cvt_pk_bf16_f32 v18, v81, v81
	v_addc_co_u32_e32 v3, vcc, 0, v67, vcc
	ds_write_b16 v246, v18 offset:256
	v_mul_f32_e32 v86, v19, v76
	v_cvt_pk_bf16_f32 v18, v86, v86
	ds_write_b16 v246, v18 offset:320
	v_mul_f32_e32 v85, v35, v76
	v_cvt_pk_bf16_f32 v18, v85, v85
	ds_write_b16 v246, v18 offset:384
	v_mul_f32_e32 v88, v51, v76
	v_cvt_pk_bf16_f32 v18, v88, v88
	ds_write_b16 v246, v18 offset:448
	v_add_co_u32_e32 v2, vcc, s45, v66
	v_mul_f32_e32 v77, v4, v78
	v_cvt_pk_bf16_f32 v4, v77, v77
	s_nop 0
	v_addc_co_u32_e32 v3, vcc, 0, v67, vcc
	ds_write_b16 v246, v4 offset:512
	v_mul_f32_e32 v83, v20, v78
	v_cvt_pk_bf16_f32 v4, v83, v83
	ds_write_b16 v246, v4 offset:576
	v_mul_f32_e32 v82, v36, v78
	v_cvt_pk_bf16_f32 v4, v82, v82
	ds_write_b16 v246, v4 offset:640
	v_mul_f32_e32 v87, v52, v78
	v_cvt_pk_bf16_f32 v4, v87, v87
	ds_write_b16 v246, v4 offset:704
	v_add_co_u32_e32 v2, vcc, s46, v66
	s_waitcnt lgkmcnt(0)
	v_rcp_f32_e32 v100, v73
	v_mul_f32_e32 v73, v5, v80
	v_cvt_pk_bf16_f32 v4, v73, v73
	v_addc_co_u32_e32 v3, vcc, 0, v67, vcc
	ds_write_b16 v246, v4 offset:768
	v_mul_f32_e32 v79, v21, v80
	v_cvt_pk_bf16_f32 v4, v79, v79
	ds_write_b16 v246, v4 offset:832
	v_mul_f32_e32 v78, v37, v80
	v_cvt_pk_bf16_f32 v4, v78, v78
	ds_write_b16 v246, v4 offset:896
	v_mul_f32_e32 v84, v53, v80
	v_cvt_pk_bf16_f32 v4, v84, v84
	ds_write_b16 v246, v4 offset:960
	v_add_co_u32_e32 v2, vcc, s47, v66
	v_rcp_f32_e32 v96, v69
	v_mul_f32_e32 v69, v6, v89
	v_cvt_pk_bf16_f32 v4, v69, v69
	v_addc_co_u32_e32 v3, vcc, 0, v67, vcc
	ds_write_b16 v246, v4 offset:2048
	v_mul_f32_e32 v75, v22, v89
	v_cvt_pk_bf16_f32 v4, v75, v75
	ds_write_b16 v246, v4 offset:2112
	v_mul_f32_e32 v74, v38, v89
	v_cvt_pk_bf16_f32 v4, v74, v74
	ds_write_b16 v246, v4 offset:2176
	v_mul_f32_e32 v80, v54, v89
	v_cvt_pk_bf16_f32 v4, v80, v80
	ds_write_b16 v246, v4 offset:2240
	v_add_co_u32_e32 v2, vcc, s48, v66
	v_mul_f32_e32 v53, v7, v90
	v_cvt_pk_bf16_f32 v4, v53, v53
	s_nop 0
	v_addc_co_u32_e32 v3, vcc, 0, v67, vcc
	v_rcp_f32_e32 v98, v71
	ds_write_b16 v246, v4 offset:2304
	v_mul_f32_e32 v71, v23, v90
	v_cvt_pk_bf16_f32 v4, v71, v71
	v_rcp_f32_e32 v97, v70
	ds_write_b16 v246, v4 offset:2368
	v_mul_f32_e32 v70, v39, v90
	v_cvt_pk_bf16_f32 v4, v70, v70
	ds_write_b16 v246, v4 offset:2432
	v_mul_f32_e32 v76, v55, v90
	v_cvt_pk_bf16_f32 v4, v76, v76
	ds_write_b16 v246, v4 offset:2496
	v_add_co_u32_e32 v2, vcc, s49, v66
	v_mul_f32_e32 v50, v8, v91
	v_cvt_pk_bf16_f32 v4, v50, v50
	s_nop 0
	v_addc_co_u32_e32 v3, vcc, 0, v67, vcc
	ds_write_b16 v246, v4 offset:2560
	v_mul_f32_e32 v55, v24, v91
	v_cvt_pk_bf16_f32 v4, v55, v55
	ds_write_b16 v246, v4 offset:2624
	v_mul_f32_e32 v54, v40, v91
	v_cvt_pk_bf16_f32 v4, v54, v54
	v_rcp_f32_e32 v99, v72
	ds_write_b16 v246, v4 offset:2688
	v_mul_f32_e32 v72, v56, v91
	v_cvt_pk_bf16_f32 v4, v72, v72
	ds_write_b16 v246, v4 offset:2752
	v_add_co_u32_e32 v2, vcc, s50, v66
	v_mul_f32_e32 v38, v9, v92
	v_cvt_pk_bf16_f32 v4, v38, v38
	s_nop 0
	v_addc_co_u32_e32 v3, vcc, 0, v67, vcc
	ds_write_b16 v246, v4 offset:2816
	v_mul_f32_e32 v52, v25, v92
	v_cvt_pk_bf16_f32 v4, v52, v52
	ds_write_b16 v246, v4 offset:2880
	v_mul_f32_e32 v51, v41, v92
	v_cvt_pk_bf16_f32 v4, v51, v51
	ds_write_b16 v246, v4 offset:2944
	v_mul_f32_e32 v56, v57, v92
	v_cvt_pk_bf16_f32 v4, v56, v56
	ds_write_b16 v246, v4 offset:3008
	v_add_co_u32_e32 v2, vcc, s24, v66
	v_mul_f32_e32 v34, v10, v93
	v_cvt_pk_bf16_f32 v4, v34, v34
	s_nop 0
	v_addc_co_u32_e32 v3, vcc, 0, v67, vcc
	ds_write_b16 v246, v4 offset:4096
; __device__ __forceinline__ int crow(int r, int hi) { return (r & 3) + 8 * (r >> 2) + 4 * hi; }
; template <int MODE, int QMODE> ...
;     ...
;   for (int r = 0; r < 16; ++r) { int orow = crow(r, hi);
; #pragma unroll
;     for (int d0 = 0; d0 < 4; ++d0) { const float v = o[d0][r] * rli[r]; Ow[(long)orow * LDO + d0 * 32] = (unsigned short)(cvtpk(v, v) & 0xffffu); o[d0][r] = v * v; } }
;   { float* hw = hsp + (long)wrow * 16 + (MODE ? (wid >> 2) : 0);
; #pragma unroll
;     for (int r = 0; r < 16; ++r) { float q = (o[0][r] + o[1][r]) + (o[2][r] + o[3][r]);
;       q += __builtin_bit_cast(float, __builtin_amdgcn_update_dpp(0, __builtin_bit_cast(int, q), 0xB1, 0xF, 0xF, true));
;       q += __builtin_bit_cast(float, __builtin_amdgcn_update_dpp(0, __builtin_bit_cast(int, q), 0x4E, 0xF, 0xF, true));
;       q += __builtin_bit_cast(float, __builtin_amdgcn_update_dpp(0, __builtin_bit_cast(int, q), 0x141, 0xF, 0xF, true));
;       q += __builtin_bit_cast(float, __builtin_amdgcn_update_dpp(0, __builtin_bit_cast(int, q), 0x140, 0xF, 0xF, true));
;       { float q2 = q; asm volatile("" : "+v"(q2)); auto rr = __builtin_amdgcn_permlane16_swap(__float_as_uint(q), __float_as_uint(q2), false, false); const unsigned a_ = rr[0], b_ = rr[1]; q = __uint_as_float(a_) + __uint_as_float(b_); }
;       if (r32e == r) hw[(long)crow(r, hi) * 16] = q; } }
	v_mul_f32_e32 v40, v26, v93
	v_cvt_pk_bf16_f32 v4, v40, v40
	ds_write_b16 v246, v4 offset:4160
	v_mul_f32_e32 v39, v42, v93
	v_cvt_pk_bf16_f32 v4, v39, v39
	ds_write_b16 v246, v4 offset:4224
	v_mul_f32_e32 v42, v58, v93
	v_cvt_pk_bf16_f32 v4, v42, v42
	ds_write_b16 v246, v4 offset:4288
	v_add_co_u32_e32 v2, vcc, s51, v66
	v_mul_f32_e32 v25, v11, v94
	v_cvt_pk_bf16_f32 v4, v25, v25
	s_nop 0
	v_addc_co_u32_e32 v3, vcc, 0, v67, vcc
	ds_write_b16 v246, v4 offset:4352
	v_mul_f32_e32 v36, v27, v94
	v_cvt_pk_bf16_f32 v4, v36, v36
	ds_write_b16 v246, v4 offset:4416
	v_mul_f32_e32 v35, v43, v94
	v_cvt_pk_bf16_f32 v4, v35, v35
	ds_write_b16 v246, v4 offset:4480
	v_mul_f32_e32 v41, v59, v94
	v_cvt_pk_bf16_f32 v4, v41, v41
	ds_write_b16 v246, v4 offset:4544
	v_add_co_u32_e32 v2, vcc, s52, v66
	v_mul_f32_e32 v21, v12, v95
	v_cvt_pk_bf16_f32 v4, v21, v21
	s_nop 0
	v_addc_co_u32_e32 v3, vcc, 0, v67, vcc
	ds_write_b16 v246, v4 offset:4608
	v_mul_f32_e32 v27, v28, v95
	v_cvt_pk_bf16_f32 v4, v27, v27
	ds_write_b16 v246, v4 offset:4672
	v_mul_f32_e32 v26, v44, v95
	v_cvt_pk_bf16_f32 v4, v26, v26
	ds_write_b16 v246, v4 offset:4736
	v_mul_f32_e32 v37, v60, v95
	v_cvt_pk_bf16_f32 v4, v37, v37
	ds_write_b16 v246, v4 offset:4800
	v_add_co_u32_e32 v2, vcc, s53, v66
	v_mul_f32_e32 v18, v13, v96
	v_cvt_pk_bf16_f32 v4, v18, v18
	s_nop 0
	v_addc_co_u32_e32 v3, vcc, 0, v67, vcc
	ds_write_b16 v246, v4 offset:4864
	v_mul_f32_e32 v23, v29, v96
	v_cvt_pk_bf16_f32 v4, v23, v23
	ds_write_b16 v246, v4 offset:4928
	v_mul_f32_e32 v22, v45, v96
	v_cvt_pk_bf16_f32 v4, v22, v22
	ds_write_b16 v246, v4 offset:4992
	v_mul_f32_e32 v28, v61, v96
	v_cvt_pk_bf16_f32 v4, v28, v28
	ds_write_b16 v246, v4 offset:5056
	v_add_co_u32_e32 v2, vcc, s54, v66
	v_mul_f32_e32 v11, v14, v97
	v_cvt_pk_bf16_f32 v4, v11, v11
	s_nop 0
	v_addc_co_u32_e32 v3, vcc, 0, v67, vcc
	ds_write_b16 v246, v4 offset:6144
	v_mul_f32_e32 v20, v30, v97
	v_cvt_pk_bf16_f32 v4, v20, v20
	ds_write_b16 v246, v4 offset:6208
	v_mul_f32_e32 v19, v46, v97
	v_cvt_pk_bf16_f32 v4, v19, v19
	ds_write_b16 v246, v4 offset:6272
	v_mul_f32_e32 v24, v62, v97
	v_cvt_pk_bf16_f32 v4, v24, v24
	ds_write_b16 v246, v4 offset:6336
	v_add_co_u32_e32 v2, vcc, s55, v66
	v_mul_f32_e32 v7, v15, v98
	v_cvt_pk_bf16_f32 v4, v7, v7
	s_nop 0
	v_addc_co_u32_e32 v3, vcc, 0, v67, vcc
	ds_write_b16 v246, v4 offset:6400
	v_mul_f32_e32 v13, v31, v98
	v_cvt_pk_bf16_f32 v4, v13, v13
	ds_write_b16 v246, v4 offset:6464
	v_mul_f32_e32 v12, v47, v98
	v_cvt_pk_bf16_f32 v4, v12, v12
	ds_write_b16 v246, v4 offset:6528
	v_mul_f32_e32 v15, v63, v98
	v_cvt_pk_bf16_f32 v4, v15, v15
	ds_write_b16 v246, v4 offset:6592
	v_add_co_u32_e32 v2, vcc, s56, v66
	v_mul_f32_e32 v4, v16, v99
	v_cvt_pk_bf16_f32 v5, v4, v4
	s_nop 0
	v_addc_co_u32_e32 v3, vcc, 0, v67, vcc
	ds_write_b16 v246, v5 offset:6656
	v_mul_f32_e32 v9, v32, v99
	v_cvt_pk_bf16_f32 v5, v9, v9
	ds_write_b16 v246, v5 offset:6720
	v_mul_f32_e32 v8, v48, v99
	v_cvt_pk_bf16_f32 v5, v8, v8
	v_add_co_u32_e32 v16, vcc, s57, v66
	ds_write_b16 v246, v5 offset:6784
	v_mul_f32_e32 v14, v64, v99
	v_cvt_pk_bf16_f32 v5, v14, v14
	ds_write_b16 v246, v5 offset:6848
	v_mul_f32_e32 v2, v17, v100
	v_cvt_pk_bf16_f32 v3, v2, v2
	v_addc_co_u32_e32 v17, vcc, 0, v67, vcc
	ds_write_b16 v246, v3 offset:6912
	v_mul_f32_e32 v6, v33, v100
	v_cvt_pk_bf16_f32 v3, v6, v6
	ds_write_b16 v246, v3 offset:6976
	v_mul_f32_e32 v5, v49, v100
	v_cvt_pk_bf16_f32 v3, v5, v5
	v_fmac_f32_e32 v102, v101, v101
	v_fmac_f32_e32 v104, v103, v103
	ds_write_b16 v246, v3 offset:7040
	v_mul_f32_e32 v10, v65, v100
	v_cvt_pk_bf16_f32 v3, v10, v10
	ds_write_b16 v246, v3 offset:7104
	v_lshl_add_u32 v247, v249, 4, s100
	v_lshrrev_b32_e32 v248, 4, v249
	v_and_b32_e32 v249, 15, v249
	v_lshlrev_b32_e32 v248, 12, v248
	v_lshl_add_u32 v248, v249, 4, v248
	s_waitcnt lgkmcnt(0)
	ds_read_b128 v[214:217], v247 offset:0
	ds_read_b128 v[218:221], v247 offset:1024
	ds_read_b128 v[222:225], v247 offset:2048
	ds_read_b128 v[226:229], v247 offset:3072
	ds_read_b128 v[230:233], v247 offset:4096
	ds_read_b128 v[234:237], v247 offset:5120
	ds_read_b128 v[238:241], v247 offset:6144
	ds_read_b128 v[242:245], v247 offset:7168
	s_waitcnt lgkmcnt(7)
	global_store_dwordx4 v248, v[214:217], s[98:99] offset:3072
	v_add_u32_e32 v248, 0x4000, v248
	s_waitcnt lgkmcnt(6)
	global_store_dwordx4 v248, v[218:221], s[98:99] offset:3072
	v_add_u32_e32 v248, 0x4000, v248
	s_waitcnt lgkmcnt(5)
	global_store_dwordx4 v248, v[222:225], s[98:99] offset:3072
	v_add_u32_e32 v248, 0x4000, v248
	s_waitcnt lgkmcnt(4)
	global_store_dwordx4 v248, v[226:229], s[98:99] offset:3072
	v_add_u32_e32 v248, 0x4000, v248
	s_waitcnt lgkmcnt(3)
	global_store_dwordx4 v248, v[230:233], s[98:99] offset:3072
	v_add_u32_e32 v248, 0x4000, v248
	s_waitcnt lgkmcnt(2)
	global_store_dwordx4 v248, v[234:237], s[98:99] offset:3072
	v_add_u32_e32 v248, 0x4000, v248
	s_waitcnt lgkmcnt(1)
	global_store_dwordx4 v248, v[238:241], s[98:99] offset:3072
	v_add_u32_e32 v248, 0x4000, v248
	s_waitcnt lgkmcnt(0)
	global_store_dwordx4 v248, v[242:245], s[98:99] offset:3072
	s_nop 1
	v_add_f32_e32 v16, v102, v104
	s_lshl_b64 s[4:5], s[16:17], 6
	s_add_u32 s2, s2, s4
	v_add_f32_dpp v16, v16, v16 quad_perm:[1,0,3,2] row_mask:0xf bank_mask:0xf bound_ctrl:1
	s_addc_u32 s3, s3, s5
	v_lshlrev_b32_e32 v3, 8, v196
	v_add_f32_dpp v16, v16, v16 quad_perm:[2,3,0,1] row_mask:0xf bank_mask:0xf bound_ctrl:1
	v_cmp_eq_u32_e32 vcc, 0, v68
	s_nop 0
	v_add_f32_dpp v16, v16, v16 row_half_mirror row_mask:0xf bank_mask:0xf bound_ctrl:1
	s_nop 1
	v_add_f32_dpp v16, v16, v16 row_mirror row_mask:0xf bank_mask:0xf bound_ctrl:1
	v_mov_b32_e32 v17, v16
	s_nop 1
	v_permlane16_swap_b32_e32 v16, v17
	s_and_saveexec_b64 s[4:5], vcc
	s_cbranch_execz .LBB0_308
	v_add_f32_e32 v16, v16, v17
	global_store_dword v3, v16, s[2:3] offset:48

; __global__ void __launch_bounds__(NWAVES * 64, 2) hymba_fwd(Params P) {
	.amdhsa_kernel _Z9hymba_fwd6Params
		.amdhsa_group_segment_fixed_size 0
		.amdhsa_private_segment_fixed_size 0
		.amdhsa_kernarg_size 416
		.amdhsa_user_sgpr_count 2
		.amdhsa_user_sgpr_dispatch_ptr 0
		.amdhsa_user_sgpr_queue_ptr 0
		.amdhsa_user_sgpr_kernarg_segment_ptr 1
		.amdhsa_user_sgpr_dispatch_id 0
		.amdhsa_user_sgpr_kernarg_preload_length 0
		.amdhsa_user_sgpr_kernarg_preload_offset 0
		.amdhsa_user_sgpr_private_segment_size 0
		.amdhsa_uses_dynamic_stack 0
		.amdhsa_enable_private_segment 0
		.amdhsa_system_sgpr_workgroup_id_x 1
		.amdhsa_system_sgpr_workgroup_id_y 0
		.amdhsa_system_sgpr_workgroup_id_z 0
		.amdhsa_system_sgpr_workgroup_info 0
		.amdhsa_system_vgpr_workitem_id 0
		.amdhsa_next_free_vgpr 255
		.amdhsa_next_free_sgpr 102
		.amdhsa_accum_offset 256
		.amdhsa_reserve_vcc 1
		.amdhsa_float_round_mode_32 0
		.amdhsa_float_round_mode_16_64 0
		.amdhsa_float_denorm_mode_32 3
		.amdhsa_float_denorm_mode_16_64 3
		.amdhsa_dx10_clamp 1
		.amdhsa_ieee_mode 1
		.amdhsa_fp16_overflow 0
		.amdhsa_tg_split 0
		.amdhsa_exception_fp_ieee_invalid_op 0
		.amdhsa_exception_fp_denorm_src 0
		.amdhsa_exception_fp_ieee_div_zero 0
		.amdhsa_exception_fp_ieee_overflow 0
		.amdhsa_exception_fp_ieee_underflow 0
		.amdhsa_exception_fp_ieee_inexact 0
		.amdhsa_exception_int_div_zero 0
	.end_amdhsa_kernel

; __global__ void __launch_bounds__(NWAVES * 64, 2) hymba_fwd(Params P) {
amdhsa.kernels:
  - .agpr_count:     0
    .args:
      - .offset:         0
        .size:           160
        .value_kind:     by_value
      - .offset:         160
        .size:           4
        .value_kind:     hidden_block_count_x
      - .offset:         164
        .size:           4
        .value_kind:     hidden_block_count_y
      - .offset:         168
        .size:           4
        .value_kind:     hidden_block_count_z
      - .offset:         172
        .size:           2
        .value_kind:     hidden_group_size_x
      - .offset:         174
        .size:           2
        .value_kind:     hidden_group_size_y
      - .offset:         176
        .size:           2
        .value_kind:     hidden_group_size_z
      - .offset:         178
        .size:           2
        .value_kind:     hidden_remainder_x
      - .offset:         180
        .size:           2
        .value_kind:     hidden_remainder_y
      - .offset:         182
        .size:           2
        .value_kind:     hidden_remainder_z
      - .offset:         200
        .size:           8
        .value_kind:     hidden_global_offset_x
      - .offset:         208
        .size:           8
        .value_kind:     hidden_global_offset_y
      - .offset:         216
        .size:           8
        .value_kind:     hidden_global_offset_z
      - .offset:         224
        .size:           2
        .value_kind:     hidden_grid_dims
      - .offset:         248
        .size:           8
        .value_kind:     hidden_multigrid_sync_arg
      - .offset:         280
        .size:           4
        .value_kind:     hidden_dynamic_lds_size
    .group_segment_fixed_size: 0
    .kernarg_segment_align: 8
    .kernarg_segment_size: 416
    .language:       OpenCL C
    .language_version:
      - 2
      - 0
    .max_flat_workgroup_size: 512
    .name:           _Z9hymba_fwd6Params
    .private_segment_fixed_size: 0
    .sgpr_count:     108
    .sgpr_spill_count: 3
    .symbol:         _Z9hymba_fwd6Params.kd
    .uniform_work_group_size: 1
    .uses_dynamic_stack: false
    .vgpr_count:     255
    .vgpr_spill_count: 0
    .wavefront_size: 64
